# v074 + attention unit epilogue: per-row 32-lane sum via DPP adds (4 of 5 ds_swizzle steps removed)
# speedup vs baseline: 1.0115x; 1.0115x over previous
; template <int K> __device__ __forceinline__ float xor_swz(float v) { return __int_as_float(__builtin_amdgcn_ds_swizzle(__float_as_int(v), (K << 10) | 0x1f)); }
; __device__ __forceinline__ int crow(int r, int hi) { return (r & 3) + 8 * (r >> 2) + 4 * hi; }
; __device__ __forceinline__ unsigned cvtpk(float lo, float hi) { unsigned r; asm volatile("v_cvt_pk_bf16_f32 %0, %1, %2" : "=v"(r) : "v"(lo), "v"(hi)); return r; }
; __device__ __forceinline__ void attn_unit(ATT_LAS unsigned char* lds, const bf16_t* Qg, const bf16_t* Kg, const bf16_t* Vg, bf16_t* Og, int b, int head, int qb, float lam, const float* subg) {
;     ...
;     float sg[4];
; #pragma unroll
;     for (int db = 0; db < 4; ++db) sg[db] = subg[32 * db + r] * 0.8f;
;     bf16_t* Ow = Og + (rowbase + q0 + wq * 32) * PITCH + head * 128 + r;
; #pragma unroll
;     for (int i = 0; i < 16; ++i) {
;         const int qr = crow(i, h); const float a1 = wsf[qr], a2 = wsf[32 + qr];
;         float o[4], ss = 0.f;
; #pragma unroll
;         for (int db = 0; db < 4; ++db) { o[db] = O1[db][i] * a1 - O2[db][i] * a2; ss += o[db] * o[db]; }
;         ss += xor_swz<1>(ss); ss += xor_swz<2>(ss); ss += xor_swz<4>(ss); ss += xor_swz<8>(ss); ss += xor_swz<16>(ss);
;         const float rs = __builtin_amdgcn_rsqf(ss * (1.0f / 128.0f) + 1e-6f);
; #pragma unroll
;         for (int db = 0; db < 4; ++db) Ow[(size_t)qr * PITCH + 32 * db] = (bf16_t)(cvtpk(o[db] * rs * sg[db], 0.f) & 0xffffu);
;     }
.LBB0_284:
	s_or_b64 exec, exec, s[4:5]
	v_lshlrev_b32_e32 v0, 2, v196
	global_load_dword v4, v0, s[40:41]
	global_load_dword v5, v0, s[40:41] offset:128
	global_load_dword v6, v0, s[40:41] offset:256
	global_load_dword v7, v0, s[40:41] offset:384
	v_lshl_add_u32 v8, v197, 2, s78
	ds_read2_b32 v[2:3], v8 offset1:32
	s_lshl_b64 s[2:3], s[90:91], 1
	s_add_u32 s2, s38, s2
	s_addc_u32 s3, s39, s3
	s_and_b64 vcc, exec, s[88:89]
	s_waitcnt lgkmcnt(0)
	v_mul_f32_e32 v9, v114, v3
	v_mul_f32_e32 v0, v130, v3
	v_fma_f32 v9, v50, v2, -v9
	v_mul_f32_e32 v10, v98, v3
	v_fma_f32 v12, v34, v2, -v0
	v_mul_f32_e32 v0, v9, v9
	v_mul_f32_e32 v3, v18, v3
	v_fma_f32 v13, v66, v2, -v10
	v_fmac_f32_e32 v0, v12, v12
	v_fma_f32 v14, v82, v2, -v3
	v_fmac_f32_e32 v0, v13, v13
	v_fmac_f32_e32 v0, v14, v14
	s_nop 1
	v_add_f32_dpp v0, v0, v0 quad_perm:[1,0,3,2] row_mask:0xf bank_mask:0xf
	s_nop 1
	v_add_f32_dpp v0, v0, v0 quad_perm:[2,3,0,1] row_mask:0xf bank_mask:0xf
	s_nop 1
	v_add_f32_dpp v0, v0, v0 row_half_mirror row_mask:0xf bank_mask:0xf
	ds_swizzle_b32 v2, v0 offset:swizzle(SWAP,8)
	s_waitcnt lgkmcnt(0)
	v_add_f32_e32 v2, v0, v2
	ds_swizzle_b32 v3, v2 offset:swizzle(SWAP,16)
	v_lshlrev_b32_e32 v0, 1, v196
	s_waitcnt lgkmcnt(0)
	v_add_f32_e32 v2, v2, v3
	v_fmamk_f32 v2, v2, 0x3c000000, v194
	v_rsq_f32_e32 v15, v2
	v_lshl_add_u64 v[2:3], s[2:3], 0, v[0:1]
	v_lshlrev_b32_e32 v0, 13, v195
	v_lshl_add_u64 v[10:11], v[2:3], 0, v[0:1]
	v_mul_f32_e32 v0, v12, v15
	v_mul_f32_e32 v9, v9, v15
	v_mul_f32_e32 v12, v13, v15
	v_mul_f32_e32 v13, v14, v15
	s_mov_b64 s[2:3], 0
	s_waitcnt vmcnt(3)
	v_mul_f32_e32 v4, 0x3f4ccccd, v4
	v_mul_f32_e32 v0, v4, v0
	s_waitcnt vmcnt(2)
	v_mul_f32_e32 v5, 0x3f4ccccd, v5
	s_waitcnt vmcnt(1)
	v_mul_f32_e32 v6, 0x3f4ccccd, v6
	s_waitcnt vmcnt(0)
	v_mul_f32_e32 v7, 0x3f4ccccd, v7
	v_cvt_pk_bf16_f32 v0, v0, v1
	v_mul_f32_e32 v9, v5, v9
	v_mul_f32_e32 v12, v6, v12
	v_mul_f32_e32 v13, v7, v13
	global_store_short v[10:11], v0, off
	v_cvt_pk_bf16_f32 v0, v9, v1
	global_store_short v[10:11], v0, off offset:64
	v_cvt_pk_bf16_f32 v0, v12, v1
	global_store_short v[10:11], v0, off offset:128
	v_cvt_pk_bf16_f32 v14, v13, v1
	ds_read2_b32 v[12:13], v8 offset0:1 offset1:33
	global_store_short v[10:11], v14, off offset:192
	s_waitcnt lgkmcnt(0)
	v_mul_f32_e32 v9, v115, v13
	v_mul_f32_e32 v0, v131, v13
	v_fma_f32 v18, v51, v12, -v9
	v_mul_f32_e32 v15, v99, v13
	v_fma_f32 v16, v35, v12, -v0
	v_mul_f32_e32 v0, v18, v18
	v_mul_f32_e32 v13, v19, v13
	v_fma_f32 v15, v67, v12, -v15
	v_fmac_f32_e32 v0, v16, v16
	v_fma_f32 v19, v83, v12, -v13
	v_fmac_f32_e32 v0, v15, v15
	v_fmac_f32_e32 v0, v19, v19
	s_nop 1
	v_add_f32_dpp v0, v0, v0 quad_perm:[1,0,3,2] row_mask:0xf bank_mask:0xf
	s_nop 1
	v_add_f32_dpp v0, v0, v0 quad_perm:[2,3,0,1] row_mask:0xf bank_mask:0xf
	s_nop 1
	v_add_f32_dpp v0, v0, v0 row_half_mirror row_mask:0xf bank_mask:0xf
	s_nop 1
	v_add_f32_dpp v0, v0, v0 row_mirror row_mask:0xf bank_mask:0xf
	ds_swizzle_b32 v12, v0 offset:swizzle(SWAP,16)
	v_lshlrev_b32_e32 v9, 11, v197
	s_waitcnt lgkmcnt(0)
	v_add_f32_e32 v0, v0, v12
	v_fmamk_f32 v0, v0, 0x3c000000, v194
	v_rsq_f32_e32 v34, v0
	v_or_b32_e32 v0, 0x800, v9
	v_lshl_add_u64 v[12:13], v[2:3], 0, v[0:1]
	v_mul_f32_e32 v0, v16, v34
	v_mul_f32_e32 v0, v4, v0
	v_mul_f32_e32 v10, v18, v34
	v_mul_f32_e32 v11, v15, v34
	v_mul_f32_e32 v14, v19, v34
	v_cvt_pk_bf16_f32 v0, v0, v1
	v_mul_f32_e32 v10, v5, v10
	v_mul_f32_e32 v11, v6, v11
	v_mul_f32_e32 v14, v7, v14
	global_store_short v[12:13], v0, off
	v_cvt_pk_bf16_f32 v0, v10, v1
	global_store_short v[12:13], v0, off offset:64
	v_cvt_pk_bf16_f32 v0, v11, v1
	global_store_short v[12:13], v0, off offset:128
	v_cvt_pk_bf16_f32 v14, v14, v1
	ds_read2_b32 v[10:11], v8 offset0:2 offset1:34
	global_store_short v[12:13], v14, off offset:192
	s_waitcnt lgkmcnt(0)
	v_mul_f32_e32 v15, v116, v11
	v_mul_f32_e32 v0, v132, v11
	v_fma_f32 v15, v52, v10, -v15
	v_mul_f32_e32 v16, v100, v11
	v_fma_f32 v18, v36, v10, -v0
	v_mul_f32_e32 v0, v15, v15
	v_mul_f32_e32 v11, v20, v11
	v_fma_f32 v16, v68, v10, -v16
	v_fmac_f32_e32 v0, v18, v18
	v_fma_f32 v19, v84, v10, -v11
	v_fmac_f32_e32 v0, v16, v16
	v_fmac_f32_e32 v0, v19, v19
	s_nop 1
	v_add_f32_dpp v0, v0, v0 quad_perm:[1,0,3,2] row_mask:0xf bank_mask:0xf
	s_nop 1
	v_add_f32_dpp v0, v0, v0 quad_perm:[2,3,0,1] row_mask:0xf bank_mask:0xf
	s_nop 1
	v_add_f32_dpp v0, v0, v0 row_half_mirror row_mask:0xf bank_mask:0xf
	s_nop 1
	v_add_f32_dpp v0, v0, v0 row_mirror row_mask:0xf bank_mask:0xf
	ds_swizzle_b32 v10, v0 offset:swizzle(SWAP,16)
	s_waitcnt lgkmcnt(0)
	v_add_f32_e32 v0, v0, v10
	v_fmamk_f32 v0, v0, 0x3c000000, v194
	v_rsq_f32_e32 v20, v0
	v_or_b32_e32 v0, 0x1000, v9
	v_lshl_add_u64 v[10:11], v[2:3], 0, v[0:1]
	v_mul_f32_e32 v0, v18, v20
	v_mul_f32_e32 v0, v4, v0
	v_mul_f32_e32 v12, v15, v20
	v_mul_f32_e32 v13, v16, v20
	v_mul_f32_e32 v14, v19, v20
	v_cvt_pk_bf16_f32 v0, v0, v1
	v_mul_f32_e32 v12, v5, v12
	v_mul_f32_e32 v13, v6, v13
	v_mul_f32_e32 v14, v7, v14
	global_store_short v[10:11], v0, off
	v_cvt_pk_bf16_f32 v0, v12, v1
	global_store_short v[10:11], v0, off offset:64
	v_cvt_pk_bf16_f32 v0, v13, v1
	global_store_short v[10:11], v0, off offset:128
	v_cvt_pk_bf16_f32 v14, v14, v1
	ds_read2_b32 v[12:13], v8 offset0:3 offset1:35
	global_store_short v[10:11], v14, off offset:192
	s_waitcnt lgkmcnt(0)
; template <int K> __device__ __forceinline__ float xor_swz(float v) { return __int_as_float(__builtin_amdgcn_ds_swizzle(__float_as_int(v), (K << 10) | 0x1f)); }
; __device__ __forceinline__ int crow(int r, int hi) { return (r & 3) + 8 * (r >> 2) + 4 * hi; }
; __device__ __forceinline__ unsigned cvtpk(float lo, float hi) { unsigned r; asm volatile("v_cvt_pk_bf16_f32 %0, %1, %2" : "=v"(r) : "v"(lo), "v"(hi)); return r; }
; __device__ __forceinline__ void attn_unit(ATT_LAS unsigned char* lds, const bf16_t* Qg, const bf16_t* Kg, const bf16_t* Vg, bf16_t* Og, int b, int head, int qb, float lam, const float* subg) {
;     ...
;     for (int i = 0; i < 16; ++i) {
;         const int qr = crow(i, h); const float a1 = wsf[qr], a2 = wsf[32 + qr];
;         float o[4], ss = 0.f;
; #pragma unroll
;         for (int db = 0; db < 4; ++db) { o[db] = O1[db][i] * a1 - O2[db][i] * a2; ss += o[db] * o[db]; }
;         ss += xor_swz<1>(ss); ss += xor_swz<2>(ss); ss += xor_swz<4>(ss); ss += xor_swz<8>(ss); ss += xor_swz<16>(ss);
;         const float rs = __builtin_amdgcn_rsqf(ss * (1.0f / 128.0f) + 1e-6f);
; #pragma unroll
;         for (int db = 0; db < 4; ++db) Ow[(size_t)qr * PITCH + 32 * db] = (bf16_t)(cvtpk(o[db] * rs * sg[db], 0.f) & 0xffffu);
;     }
	v_mul_f32_e32 v15, v117, v13
	v_mul_f32_e32 v0, v133, v13
	v_fma_f32 v15, v53, v12, -v15
	v_mul_f32_e32 v16, v101, v13
	v_fma_f32 v18, v37, v12, -v0
	v_mul_f32_e32 v0, v15, v15
	v_mul_f32_e32 v13, v21, v13
	v_fma_f32 v16, v69, v12, -v16
	v_fmac_f32_e32 v0, v18, v18
	v_fma_f32 v19, v85, v12, -v13
	v_fmac_f32_e32 v0, v16, v16
	v_fmac_f32_e32 v0, v19, v19
	s_nop 1
	v_add_f32_dpp v0, v0, v0 quad_perm:[1,0,3,2] row_mask:0xf bank_mask:0xf
	s_nop 1
	v_add_f32_dpp v0, v0, v0 quad_perm:[2,3,0,1] row_mask:0xf bank_mask:0xf
	s_nop 1
	v_add_f32_dpp v0, v0, v0 row_half_mirror row_mask:0xf bank_mask:0xf
	s_nop 1
	v_add_f32_dpp v0, v0, v0 row_mirror row_mask:0xf bank_mask:0xf
	ds_swizzle_b32 v12, v0 offset:swizzle(SWAP,16)
	s_waitcnt lgkmcnt(0)
	v_add_f32_e32 v0, v0, v12
	v_fmamk_f32 v0, v0, 0x3c000000, v194
	v_rsq_f32_e32 v20, v0
	v_or_b32_e32 v0, 0x1800, v9
	v_lshl_add_u64 v[12:13], v[2:3], 0, v[0:1]
	v_mul_f32_e32 v0, v18, v20
	v_mul_f32_e32 v0, v4, v0
	v_mul_f32_e32 v10, v15, v20
	v_mul_f32_e32 v11, v16, v20
	v_mul_f32_e32 v14, v19, v20
	v_cvt_pk_bf16_f32 v0, v0, v1
	v_mul_f32_e32 v10, v5, v10
	v_mul_f32_e32 v11, v6, v11
	v_mul_f32_e32 v14, v7, v14
	global_store_short v[12:13], v0, off
	v_cvt_pk_bf16_f32 v0, v10, v1
	global_store_short v[12:13], v0, off offset:64
	v_cvt_pk_bf16_f32 v0, v11, v1
	global_store_short v[12:13], v0, off offset:128
	v_cvt_pk_bf16_f32 v14, v14, v1
	ds_read2_b32 v[10:11], v8 offset0:8 offset1:40
	global_store_short v[12:13], v14, off offset:192
	s_waitcnt lgkmcnt(0)
	v_mul_f32_e32 v15, v118, v11
	v_mul_f32_e32 v0, v134, v11
	v_fma_f32 v15, v54, v10, -v15
	v_mul_f32_e32 v16, v102, v11
	v_fma_f32 v18, v38, v10, -v0
	v_mul_f32_e32 v0, v15, v15
	v_mul_f32_e32 v11, v22, v11
	v_fma_f32 v16, v70, v10, -v16
	v_fmac_f32_e32 v0, v18, v18
	v_fma_f32 v19, v86, v10, -v11
	v_fmac_f32_e32 v0, v16, v16
	v_fmac_f32_e32 v0, v19, v19
	s_nop 1
	v_add_f32_dpp v0, v0, v0 quad_perm:[1,0,3,2] row_mask:0xf bank_mask:0xf
	s_nop 1
	v_add_f32_dpp v0, v0, v0 quad_perm:[2,3,0,1] row_mask:0xf bank_mask:0xf
	s_nop 1
	v_add_f32_dpp v0, v0, v0 row_half_mirror row_mask:0xf bank_mask:0xf
	s_nop 1
	v_add_f32_dpp v0, v0, v0 row_mirror row_mask:0xf bank_mask:0xf
	ds_swizzle_b32 v10, v0 offset:swizzle(SWAP,16)
	s_waitcnt lgkmcnt(0)
	v_add_f32_e32 v0, v0, v10
	v_fmamk_f32 v0, v0, 0x3c000000, v194
	v_rsq_f32_e32 v20, v0
	v_or_b32_e32 v0, 0x4000, v9
	v_lshl_add_u64 v[10:11], v[2:3], 0, v[0:1]
	v_mul_f32_e32 v0, v18, v20
	v_mul_f32_e32 v0, v4, v0
	v_mul_f32_e32 v12, v15, v20
	v_mul_f32_e32 v13, v16, v20
	v_mul_f32_e32 v14, v19, v20
	v_cvt_pk_bf16_f32 v0, v0, v1
	v_mul_f32_e32 v12, v5, v12
	v_mul_f32_e32 v13, v6, v13
	v_mul_f32_e32 v14, v7, v14
	global_store_short v[10:11], v0, off
	v_cvt_pk_bf16_f32 v0, v12, v1
	global_store_short v[10:11], v0, off offset:64
	v_cvt_pk_bf16_f32 v0, v13, v1
	global_store_short v[10:11], v0, off offset:128
	v_cvt_pk_bf16_f32 v14, v14, v1
	ds_read2_b32 v[12:13], v8 offset0:9 offset1:41
	global_store_short v[10:11], v14, off offset:192
	s_waitcnt lgkmcnt(0)
	v_mul_f32_e32 v15, v119, v13
	v_mul_f32_e32 v0, v135, v13
	v_fma_f32 v15, v55, v12, -v15
	v_mul_f32_e32 v16, v103, v13
	v_fma_f32 v18, v39, v12, -v0
	v_mul_f32_e32 v0, v15, v15
	v_mul_f32_e32 v13, v23, v13
	v_fma_f32 v16, v71, v12, -v16
	v_fmac_f32_e32 v0, v18, v18
	v_fma_f32 v19, v87, v12, -v13
	v_fmac_f32_e32 v0, v16, v16
	v_fmac_f32_e32 v0, v19, v19
	s_nop 1
	v_add_f32_dpp v0, v0, v0 quad_perm:[1,0,3,2] row_mask:0xf bank_mask:0xf
	s_nop 1
	v_add_f32_dpp v0, v0, v0 quad_perm:[2,3,0,1] row_mask:0xf bank_mask:0xf
	s_nop 1
	v_add_f32_dpp v0, v0, v0 row_half_mirror row_mask:0xf bank_mask:0xf
	s_nop 1
	v_add_f32_dpp v0, v0, v0 row_mirror row_mask:0xf bank_mask:0xf
	ds_swizzle_b32 v12, v0 offset:swizzle(SWAP,16)
	s_waitcnt lgkmcnt(0)
	v_add_f32_e32 v0, v0, v12
	v_fmamk_f32 v0, v0, 0x3c000000, v194
	v_rsq_f32_e32 v20, v0
	v_or_b32_e32 v0, 0x4800, v9
	v_lshl_add_u64 v[12:13], v[2:3], 0, v[0:1]
	v_mul_f32_e32 v0, v18, v20
	v_mul_f32_e32 v0, v4, v0
	v_mul_f32_e32 v10, v15, v20
	v_mul_f32_e32 v11, v16, v20
	v_mul_f32_e32 v14, v19, v20
	v_cvt_pk_bf16_f32 v0, v0, v1
	v_mul_f32_e32 v10, v5, v10
	v_mul_f32_e32 v11, v6, v11
	v_mul_f32_e32 v14, v7, v14
	global_store_short v[12:13], v0, off
	v_cvt_pk_bf16_f32 v0, v10, v1
	global_store_short v[12:13], v0, off offset:64
	v_cvt_pk_bf16_f32 v0, v11, v1
	global_store_short v[12:13], v0, off offset:128
	v_cvt_pk_bf16_f32 v14, v14, v1
	ds_read2_b32 v[10:11], v8 offset0:10 offset1:42
	global_store_short v[12:13], v14, off offset:192
	s_waitcnt lgkmcnt(0)
	v_mul_f32_e32 v15, v120, v11
	v_mul_f32_e32 v0, v136, v11
	v_fma_f32 v15, v56, v10, -v15
	v_mul_f32_e32 v16, v104, v11
	v_fma_f32 v18, v40, v10, -v0
	v_mul_f32_e32 v0, v15, v15
	v_mul_f32_e32 v11, v24, v11
	v_fma_f32 v16, v72, v10, -v16
	v_fmac_f32_e32 v0, v18, v18
	v_fma_f32 v19, v88, v10, -v11
	v_fmac_f32_e32 v0, v16, v16
	v_fmac_f32_e32 v0, v19, v19
	s_nop 1
	v_add_f32_dpp v0, v0, v0 quad_perm:[1,0,3,2] row_mask:0xf bank_mask:0xf
	s_nop 1
	v_add_f32_dpp v0, v0, v0 quad_perm:[2,3,0,1] row_mask:0xf bank_mask:0xf
	s_nop 1
	v_add_f32_dpp v0, v0, v0 row_half_mirror row_mask:0xf bank_mask:0xf
	s_nop 1
	v_add_f32_dpp v0, v0, v0 row_mirror row_mask:0xf bank_mask:0xf
	ds_swizzle_b32 v10, v0 offset:swizzle(SWAP,16)
	s_waitcnt lgkmcnt(0)
; template <int K> __device__ __forceinline__ float xor_swz(float v) { return __int_as_float(__builtin_amdgcn_ds_swizzle(__float_as_int(v), (K << 10) | 0x1f)); }
; __device__ __forceinline__ int crow(int r, int hi) { return (r & 3) + 8 * (r >> 2) + 4 * hi; }
; __device__ __forceinline__ unsigned cvtpk(float lo, float hi) { unsigned r; asm volatile("v_cvt_pk_bf16_f32 %0, %1, %2" : "=v"(r) : "v"(lo), "v"(hi)); return r; }
; __device__ __forceinline__ void attn_unit(ATT_LAS unsigned char* lds, const bf16_t* Qg, const bf16_t* Kg, const bf16_t* Vg, bf16_t* Og, int b, int head, int qb, float lam, const float* subg) {
;     ...
;     for (int i = 0; i < 16; ++i) {
;         const int qr = crow(i, h); const float a1 = wsf[qr], a2 = wsf[32 + qr];
;         float o[4], ss = 0.f;
; #pragma unroll
;         for (int db = 0; db < 4; ++db) { o[db] = O1[db][i] * a1 - O2[db][i] * a2; ss += o[db] * o[db]; }
;         ss += xor_swz<1>(ss); ss += xor_swz<2>(ss); ss += xor_swz<4>(ss); ss += xor_swz<8>(ss); ss += xor_swz<16>(ss);
;         const float rs = __builtin_amdgcn_rsqf(ss * (1.0f / 128.0f) + 1e-6f);
; #pragma unroll
;         for (int db = 0; db < 4; ++db) Ow[(size_t)qr * PITCH + 32 * db] = (bf16_t)(cvtpk(o[db] * rs * sg[db], 0.f) & 0xffffu);
;     }
	v_add_f32_e32 v0, v0, v10
	v_fmamk_f32 v0, v0, 0x3c000000, v194
	v_rsq_f32_e32 v20, v0
	v_or_b32_e32 v0, 0x5000, v9
	v_lshl_add_u64 v[10:11], v[2:3], 0, v[0:1]
	v_mul_f32_e32 v0, v18, v20
	v_mul_f32_e32 v0, v4, v0
	v_mul_f32_e32 v12, v15, v20
	v_mul_f32_e32 v13, v16, v20
	v_mul_f32_e32 v14, v19, v20
	v_cvt_pk_bf16_f32 v0, v0, v1
	v_mul_f32_e32 v12, v5, v12
	v_mul_f32_e32 v13, v6, v13
	v_mul_f32_e32 v14, v7, v14
	global_store_short v[10:11], v0, off
	v_cvt_pk_bf16_f32 v0, v12, v1
	global_store_short v[10:11], v0, off offset:64
	v_cvt_pk_bf16_f32 v0, v13, v1
	global_store_short v[10:11], v0, off offset:128
	v_cvt_pk_bf16_f32 v14, v14, v1
	ds_read2_b32 v[12:13], v8 offset0:11 offset1:43
	global_store_short v[10:11], v14, off offset:192
	s_waitcnt lgkmcnt(0)
	v_mul_f32_e32 v15, v121, v13
	v_mul_f32_e32 v0, v137, v13
	v_fma_f32 v15, v57, v12, -v15
	v_mul_f32_e32 v16, v105, v13
	v_fma_f32 v18, v41, v12, -v0
	v_mul_f32_e32 v0, v15, v15
	v_mul_f32_e32 v13, v25, v13
	v_fma_f32 v16, v73, v12, -v16
	v_fmac_f32_e32 v0, v18, v18
	v_fma_f32 v19, v89, v12, -v13
	v_fmac_f32_e32 v0, v16, v16
	v_fmac_f32_e32 v0, v19, v19
	s_nop 1
	v_add_f32_dpp v0, v0, v0 quad_perm:[1,0,3,2] row_mask:0xf bank_mask:0xf
	s_nop 1
	v_add_f32_dpp v0, v0, v0 quad_perm:[2,3,0,1] row_mask:0xf bank_mask:0xf
	s_nop 1
	v_add_f32_dpp v0, v0, v0 row_half_mirror row_mask:0xf bank_mask:0xf
	s_nop 1
	v_add_f32_dpp v0, v0, v0 row_mirror row_mask:0xf bank_mask:0xf
	ds_swizzle_b32 v12, v0 offset:swizzle(SWAP,16)
	s_waitcnt lgkmcnt(0)
	v_add_f32_e32 v0, v0, v12
	v_fmamk_f32 v0, v0, 0x3c000000, v194
	v_rsq_f32_e32 v20, v0
	v_or_b32_e32 v0, 0x5800, v9
	v_lshl_add_u64 v[12:13], v[2:3], 0, v[0:1]
	v_mul_f32_e32 v0, v18, v20
	v_mul_f32_e32 v0, v4, v0
	v_mul_f32_e32 v10, v15, v20
	v_mul_f32_e32 v11, v16, v20
	v_mul_f32_e32 v14, v19, v20
	v_cvt_pk_bf16_f32 v0, v0, v1
	v_mul_f32_e32 v10, v5, v10
	v_mul_f32_e32 v11, v6, v11
	v_mul_f32_e32 v14, v7, v14
	global_store_short v[12:13], v0, off
	v_cvt_pk_bf16_f32 v0, v10, v1
	global_store_short v[12:13], v0, off offset:64
	v_cvt_pk_bf16_f32 v0, v11, v1
	global_store_short v[12:13], v0, off offset:128
	v_cvt_pk_bf16_f32 v14, v14, v1
	ds_read2_b32 v[10:11], v8 offset0:16 offset1:48
	global_store_short v[12:13], v14, off offset:192
	s_waitcnt lgkmcnt(0)
	v_mul_f32_e32 v15, v122, v11
	v_mul_f32_e32 v0, v138, v11
	v_fma_f32 v15, v58, v10, -v15
	v_mul_f32_e32 v16, v106, v11
	v_fma_f32 v18, v42, v10, -v0
	v_mul_f32_e32 v0, v15, v15
	v_mul_f32_e32 v11, v26, v11
	v_fma_f32 v16, v74, v10, -v16
	v_fmac_f32_e32 v0, v18, v18
	v_fma_f32 v19, v90, v10, -v11
	v_fmac_f32_e32 v0, v16, v16
	v_fmac_f32_e32 v0, v19, v19
	s_nop 1
	v_add_f32_dpp v0, v0, v0 quad_perm:[1,0,3,2] row_mask:0xf bank_mask:0xf
	s_nop 1
	v_add_f32_dpp v0, v0, v0 quad_perm:[2,3,0,1] row_mask:0xf bank_mask:0xf
	s_nop 1
	v_add_f32_dpp v0, v0, v0 row_half_mirror row_mask:0xf bank_mask:0xf
	s_nop 1
	v_add_f32_dpp v0, v0, v0 row_mirror row_mask:0xf bank_mask:0xf
	ds_swizzle_b32 v10, v0 offset:swizzle(SWAP,16)
	s_waitcnt lgkmcnt(0)
	v_add_f32_e32 v0, v0, v10
	v_fmamk_f32 v0, v0, 0x3c000000, v194
	v_rsq_f32_e32 v20, v0
	v_or_b32_e32 v0, 0x8000, v9
	v_lshl_add_u64 v[10:11], v[2:3], 0, v[0:1]
	v_mul_f32_e32 v0, v18, v20
	v_mul_f32_e32 v0, v4, v0
	v_mul_f32_e32 v12, v15, v20
	v_mul_f32_e32 v13, v16, v20
	v_mul_f32_e32 v14, v19, v20
	v_cvt_pk_bf16_f32 v0, v0, v1
	v_mul_f32_e32 v12, v5, v12
	v_mul_f32_e32 v13, v6, v13
	v_mul_f32_e32 v14, v7, v14
	global_store_short v[10:11], v0, off
	v_cvt_pk_bf16_f32 v0, v12, v1
	global_store_short v[10:11], v0, off offset:64
	v_cvt_pk_bf16_f32 v0, v13, v1
	global_store_short v[10:11], v0, off offset:128
	v_cvt_pk_bf16_f32 v14, v14, v1
	ds_read2_b32 v[12:13], v8 offset0:17 offset1:49
	global_store_short v[10:11], v14, off offset:192
	s_waitcnt lgkmcnt(0)
	v_mul_f32_e32 v15, v123, v13
	v_mul_f32_e32 v0, v139, v13
	v_fma_f32 v15, v59, v12, -v15
	v_mul_f32_e32 v16, v107, v13
	v_fma_f32 v18, v43, v12, -v0
	v_mul_f32_e32 v0, v15, v15
	v_mul_f32_e32 v13, v27, v13
	v_fma_f32 v16, v75, v12, -v16
	v_fmac_f32_e32 v0, v18, v18
	v_fma_f32 v19, v91, v12, -v13
	v_fmac_f32_e32 v0, v16, v16
	v_fmac_f32_e32 v0, v19, v19
	s_nop 1
	v_add_f32_dpp v0, v0, v0 quad_perm:[1,0,3,2] row_mask:0xf bank_mask:0xf
	s_nop 1
	v_add_f32_dpp v0, v0, v0 quad_perm:[2,3,0,1] row_mask:0xf bank_mask:0xf
	s_nop 1
	v_add_f32_dpp v0, v0, v0 row_half_mirror row_mask:0xf bank_mask:0xf
	s_nop 1
	v_add_f32_dpp v0, v0, v0 row_mirror row_mask:0xf bank_mask:0xf
	ds_swizzle_b32 v12, v0 offset:swizzle(SWAP,16)
	s_waitcnt lgkmcnt(0)
	v_add_f32_e32 v0, v0, v12
	v_fmamk_f32 v0, v0, 0x3c000000, v194
	v_rsq_f32_e32 v20, v0
	v_or_b32_e32 v0, 0x8800, v9
	v_lshl_add_u64 v[12:13], v[2:3], 0, v[0:1]
	v_mul_f32_e32 v0, v18, v20
	v_mul_f32_e32 v0, v4, v0
	v_mul_f32_e32 v10, v15, v20
	v_mul_f32_e32 v11, v16, v20
	v_mul_f32_e32 v14, v19, v20
	v_cvt_pk_bf16_f32 v0, v0, v1
	v_mul_f32_e32 v10, v5, v10
	v_mul_f32_e32 v11, v6, v11
	v_mul_f32_e32 v14, v7, v14
	global_store_short v[12:13], v0, off
	v_cvt_pk_bf16_f32 v0, v10, v1
	global_store_short v[12:13], v0, off offset:64
	v_cvt_pk_bf16_f32 v0, v11, v1
	global_store_short v[12:13], v0, off offset:128
	v_cvt_pk_bf16_f32 v14, v14, v1
	ds_read2_b32 v[10:11], v8 offset0:18 offset1:50
	global_store_short v[12:13], v14, off offset:192
	s_waitcnt lgkmcnt(0)
; template <int K> __device__ __forceinline__ float xor_swz(float v) { return __int_as_float(__builtin_amdgcn_ds_swizzle(__float_as_int(v), (K << 10) | 0x1f)); }
; __device__ __forceinline__ int crow(int r, int hi) { return (r & 3) + 8 * (r >> 2) + 4 * hi; }
; __device__ __forceinline__ unsigned cvtpk(float lo, float hi) { unsigned r; asm volatile("v_cvt_pk_bf16_f32 %0, %1, %2" : "=v"(r) : "v"(lo), "v"(hi)); return r; }
; __device__ __forceinline__ void attn_unit(ATT_LAS unsigned char* lds, const bf16_t* Qg, const bf16_t* Kg, const bf16_t* Vg, bf16_t* Og, int b, int head, int qb, float lam, const float* subg) {
;     ...
;     for (int i = 0; i < 16; ++i) {
;         const int qr = crow(i, h); const float a1 = wsf[qr], a2 = wsf[32 + qr];
;         float o[4], ss = 0.f;
; #pragma unroll
;         for (int db = 0; db < 4; ++db) { o[db] = O1[db][i] * a1 - O2[db][i] * a2; ss += o[db] * o[db]; }
;         ss += xor_swz<1>(ss); ss += xor_swz<2>(ss); ss += xor_swz<4>(ss); ss += xor_swz<8>(ss); ss += xor_swz<16>(ss);
;         const float rs = __builtin_amdgcn_rsqf(ss * (1.0f / 128.0f) + 1e-6f);
; #pragma unroll
;         for (int db = 0; db < 4; ++db) Ow[(size_t)qr * PITCH + 32 * db] = (bf16_t)(cvtpk(o[db] * rs * sg[db], 0.f) & 0xffffu);
;     }
	v_mul_f32_e32 v15, v124, v11
	v_mul_f32_e32 v0, v140, v11
	v_fma_f32 v15, v60, v10, -v15
	v_mul_f32_e32 v16, v108, v11
	v_fma_f32 v18, v44, v10, -v0
	v_mul_f32_e32 v0, v15, v15
	v_mul_f32_e32 v11, v28, v11
	v_fma_f32 v16, v76, v10, -v16
	v_fmac_f32_e32 v0, v18, v18
	v_fma_f32 v19, v92, v10, -v11
	v_fmac_f32_e32 v0, v16, v16
	v_fmac_f32_e32 v0, v19, v19
	s_nop 1
	v_add_f32_dpp v0, v0, v0 quad_perm:[1,0,3,2] row_mask:0xf bank_mask:0xf
	s_nop 1
	v_add_f32_dpp v0, v0, v0 quad_perm:[2,3,0,1] row_mask:0xf bank_mask:0xf
	s_nop 1
	v_add_f32_dpp v0, v0, v0 row_half_mirror row_mask:0xf bank_mask:0xf
	s_nop 1
	v_add_f32_dpp v0, v0, v0 row_mirror row_mask:0xf bank_mask:0xf
	ds_swizzle_b32 v10, v0 offset:swizzle(SWAP,16)
	s_waitcnt lgkmcnt(0)
	v_add_f32_e32 v0, v0, v10
	v_fmamk_f32 v0, v0, 0x3c000000, v194
	v_rsq_f32_e32 v20, v0
	v_or_b32_e32 v0, 0x9000, v9
	v_lshl_add_u64 v[10:11], v[2:3], 0, v[0:1]
	v_mul_f32_e32 v0, v18, v20
	v_mul_f32_e32 v0, v4, v0
	v_mul_f32_e32 v12, v15, v20
	v_mul_f32_e32 v13, v16, v20
	v_mul_f32_e32 v14, v19, v20
	v_cvt_pk_bf16_f32 v0, v0, v1
	v_mul_f32_e32 v12, v5, v12
	v_mul_f32_e32 v13, v6, v13
	v_mul_f32_e32 v14, v7, v14
	global_store_short v[10:11], v0, off
	v_cvt_pk_bf16_f32 v0, v12, v1
	global_store_short v[10:11], v0, off offset:64
	v_cvt_pk_bf16_f32 v0, v13, v1
	global_store_short v[10:11], v0, off offset:128
	v_cvt_pk_bf16_f32 v14, v14, v1
	ds_read2_b32 v[12:13], v8 offset0:19 offset1:51
	global_store_short v[10:11], v14, off offset:192
	s_waitcnt lgkmcnt(0)
	v_mul_f32_e32 v15, v125, v13
	v_mul_f32_e32 v0, v141, v13
	v_fma_f32 v15, v61, v12, -v15
	v_mul_f32_e32 v16, v109, v13
	v_fma_f32 v18, v45, v12, -v0
	v_mul_f32_e32 v0, v15, v15
	v_mul_f32_e32 v13, v29, v13
	v_fma_f32 v16, v77, v12, -v16
	v_fmac_f32_e32 v0, v18, v18
	v_fma_f32 v19, v93, v12, -v13
	v_fmac_f32_e32 v0, v16, v16
	v_fmac_f32_e32 v0, v19, v19
	s_nop 1
	v_add_f32_dpp v0, v0, v0 quad_perm:[1,0,3,2] row_mask:0xf bank_mask:0xf
	s_nop 1
	v_add_f32_dpp v0, v0, v0 quad_perm:[2,3,0,1] row_mask:0xf bank_mask:0xf
	s_nop 1
	v_add_f32_dpp v0, v0, v0 row_half_mirror row_mask:0xf bank_mask:0xf
	s_nop 1
	v_add_f32_dpp v0, v0, v0 row_mirror row_mask:0xf bank_mask:0xf
	ds_swizzle_b32 v12, v0 offset:swizzle(SWAP,16)
	s_waitcnt lgkmcnt(0)
	v_add_f32_e32 v0, v0, v12
	v_fmamk_f32 v0, v0, 0x3c000000, v194
	v_rsq_f32_e32 v20, v0
	v_or_b32_e32 v0, 0x9800, v9
	v_lshl_add_u64 v[12:13], v[2:3], 0, v[0:1]
	v_mul_f32_e32 v0, v18, v20
	v_mul_f32_e32 v0, v4, v0
	v_mul_f32_e32 v10, v15, v20
	v_mul_f32_e32 v11, v16, v20
	v_mul_f32_e32 v14, v19, v20
	v_cvt_pk_bf16_f32 v0, v0, v1
	v_mul_f32_e32 v10, v5, v10
	v_mul_f32_e32 v11, v6, v11
	v_mul_f32_e32 v14, v7, v14
	global_store_short v[12:13], v0, off
	v_cvt_pk_bf16_f32 v0, v10, v1
	global_store_short v[12:13], v0, off offset:64
	v_cvt_pk_bf16_f32 v0, v11, v1
	global_store_short v[12:13], v0, off offset:128
	v_cvt_pk_bf16_f32 v14, v14, v1
	ds_read2_b32 v[10:11], v8 offset0:24 offset1:56
	global_store_short v[12:13], v14, off offset:192
	s_waitcnt lgkmcnt(0)
	v_mul_f32_e32 v15, v126, v11
	v_mul_f32_e32 v0, v142, v11
	v_fma_f32 v15, v62, v10, -v15
	v_mul_f32_e32 v16, v110, v11
	v_fma_f32 v18, v46, v10, -v0
	v_mul_f32_e32 v0, v15, v15
	v_mul_f32_e32 v11, v30, v11
	v_fma_f32 v16, v78, v10, -v16
	v_fmac_f32_e32 v0, v18, v18
	v_fma_f32 v19, v94, v10, -v11
	v_fmac_f32_e32 v0, v16, v16
	v_fmac_f32_e32 v0, v19, v19
	s_nop 1
	v_add_f32_dpp v0, v0, v0 quad_perm:[1,0,3,2] row_mask:0xf bank_mask:0xf
	s_nop 1
	v_add_f32_dpp v0, v0, v0 quad_perm:[2,3,0,1] row_mask:0xf bank_mask:0xf
	s_nop 1
	v_add_f32_dpp v0, v0, v0 row_half_mirror row_mask:0xf bank_mask:0xf
	s_nop 1
	v_add_f32_dpp v0, v0, v0 row_mirror row_mask:0xf bank_mask:0xf
	ds_swizzle_b32 v10, v0 offset:swizzle(SWAP,16)
	s_waitcnt lgkmcnt(0)
	v_add_f32_e32 v0, v0, v10
	v_fmamk_f32 v0, v0, 0x3c000000, v194
	v_rsq_f32_e32 v20, v0
	v_or_b32_e32 v0, 0xc000, v9
	v_lshl_add_u64 v[10:11], v[2:3], 0, v[0:1]
	v_mul_f32_e32 v0, v18, v20
	v_mul_f32_e32 v0, v4, v0
	v_mul_f32_e32 v12, v15, v20
	v_mul_f32_e32 v13, v16, v20
	v_mul_f32_e32 v14, v19, v20
	v_cvt_pk_bf16_f32 v0, v0, v1
	v_mul_f32_e32 v12, v5, v12
	v_mul_f32_e32 v13, v6, v13
	v_mul_f32_e32 v14, v7, v14
	global_store_short v[10:11], v0, off
	v_cvt_pk_bf16_f32 v0, v12, v1
	global_store_short v[10:11], v0, off offset:64
	v_cvt_pk_bf16_f32 v0, v13, v1
	global_store_short v[10:11], v0, off offset:128
	v_cvt_pk_bf16_f32 v14, v14, v1
	ds_read2_b32 v[12:13], v8 offset0:25 offset1:57
	global_store_short v[10:11], v14, off offset:192
	s_waitcnt lgkmcnt(0)
; template <int K> __device__ __forceinline__ float xor_swz(float v) { return __int_as_float(__builtin_amdgcn_ds_swizzle(__float_as_int(v), (K << 10) | 0x1f)); }
; __device__ __forceinline__ int crow(int r, int hi) { return (r & 3) + 8 * (r >> 2) + 4 * hi; }
; __device__ __forceinline__ unsigned cvtpk(float lo, float hi) { unsigned r; asm volatile("v_cvt_pk_bf16_f32 %0, %1, %2" : "=v"(r) : "v"(lo), "v"(hi)); return r; }
; __device__ __forceinline__ void attn_unit(ATT_LAS unsigned char* lds, const bf16_t* Qg, const bf16_t* Kg, const bf16_t* Vg, bf16_t* Og, int b, int head, int qb, float lam, const float* subg) {
;     ...
;     for (int i = 0; i < 16; ++i) {
;         const int qr = crow(i, h); const float a1 = wsf[qr], a2 = wsf[32 + qr];
;         float o[4], ss = 0.f;
; #pragma unroll
;         for (int db = 0; db < 4; ++db) { o[db] = O1[db][i] * a1 - O2[db][i] * a2; ss += o[db] * o[db]; }
;         ss += xor_swz<1>(ss); ss += xor_swz<2>(ss); ss += xor_swz<4>(ss); ss += xor_swz<8>(ss); ss += xor_swz<16>(ss);
;         const float rs = __builtin_amdgcn_rsqf(ss * (1.0f / 128.0f) + 1e-6f);
; #pragma unroll
;         for (int db = 0; db < 4; ++db) Ow[(size_t)qr * PITCH + 32 * db] = (bf16_t)(cvtpk(o[db] * rs * sg[db], 0.f) & 0xffffu);
;     }
	v_mul_f32_e32 v15, v127, v13
	v_mul_f32_e32 v0, v143, v13
	v_fma_f32 v15, v63, v12, -v15
	v_mul_f32_e32 v16, v111, v13
	v_fma_f32 v18, v47, v12, -v0
	v_mul_f32_e32 v0, v15, v15
	v_mul_f32_e32 v13, v31, v13
	v_fma_f32 v16, v79, v12, -v16
	v_fmac_f32_e32 v0, v18, v18
	v_fma_f32 v19, v95, v12, -v13
	v_fmac_f32_e32 v0, v16, v16
	v_fmac_f32_e32 v0, v19, v19
	s_nop 1
	v_add_f32_dpp v0, v0, v0 quad_perm:[1,0,3,2] row_mask:0xf bank_mask:0xf
	s_nop 1
	v_add_f32_dpp v0, v0, v0 quad_perm:[2,3,0,1] row_mask:0xf bank_mask:0xf
	s_nop 1
	v_add_f32_dpp v0, v0, v0 row_half_mirror row_mask:0xf bank_mask:0xf
	s_nop 1
	v_add_f32_dpp v0, v0, v0 row_mirror row_mask:0xf bank_mask:0xf
	ds_swizzle_b32 v12, v0 offset:swizzle(SWAP,16)
	s_waitcnt lgkmcnt(0)
	v_add_f32_e32 v0, v0, v12
	v_fmamk_f32 v0, v0, 0x3c000000, v194
	v_rsq_f32_e32 v20, v0
	v_or_b32_e32 v0, 0xc800, v9
	v_lshl_add_u64 v[12:13], v[2:3], 0, v[0:1]
	v_mul_f32_e32 v0, v18, v20
	v_mul_f32_e32 v0, v4, v0
	v_mul_f32_e32 v10, v15, v20
	v_mul_f32_e32 v11, v16, v20
	v_mul_f32_e32 v14, v19, v20
	v_cvt_pk_bf16_f32 v0, v0, v1
	v_mul_f32_e32 v10, v5, v10
	v_mul_f32_e32 v11, v6, v11
	v_mul_f32_e32 v14, v7, v14
	global_store_short v[12:13], v0, off
	v_cvt_pk_bf16_f32 v0, v10, v1
	global_store_short v[12:13], v0, off offset:64
	v_cvt_pk_bf16_f32 v0, v11, v1
	global_store_short v[12:13], v0, off offset:128
	v_cvt_pk_bf16_f32 v14, v14, v1
	ds_read2_b32 v[10:11], v8 offset0:26 offset1:58
	global_store_short v[12:13], v14, off offset:192
	s_waitcnt lgkmcnt(0)
	v_mul_f32_e32 v15, v128, v11
	v_mul_f32_e32 v0, v144, v11
	v_fma_f32 v15, v64, v10, -v15
	v_mul_f32_e32 v16, v112, v11
	v_fma_f32 v18, v48, v10, -v0
	v_mul_f32_e32 v0, v15, v15
	v_mul_f32_e32 v11, v32, v11
	v_fma_f32 v16, v80, v10, -v16
	v_fmac_f32_e32 v0, v18, v18
	v_fma_f32 v19, v96, v10, -v11
	v_fmac_f32_e32 v0, v16, v16
	v_fmac_f32_e32 v0, v19, v19
	s_nop 1
	v_add_f32_dpp v0, v0, v0 quad_perm:[1,0,3,2] row_mask:0xf bank_mask:0xf
	s_nop 1
	v_add_f32_dpp v0, v0, v0 quad_perm:[2,3,0,1] row_mask:0xf bank_mask:0xf
	s_nop 1
	v_add_f32_dpp v0, v0, v0 row_half_mirror row_mask:0xf bank_mask:0xf
	s_nop 1
	v_add_f32_dpp v0, v0, v0 row_mirror row_mask:0xf bank_mask:0xf
	ds_swizzle_b32 v10, v0 offset:swizzle(SWAP,16)
	s_waitcnt lgkmcnt(0)
	v_add_f32_e32 v0, v0, v10
	v_fmamk_f32 v0, v0, 0x3c000000, v194
	v_rsq_f32_e32 v20, v0
	v_or_b32_e32 v0, 0xd000, v9
	v_lshl_add_u64 v[10:11], v[2:3], 0, v[0:1]
	v_mul_f32_e32 v0, v18, v20
	v_mul_f32_e32 v0, v4, v0
	v_mul_f32_e32 v12, v15, v20
	v_mul_f32_e32 v13, v16, v20
	v_mul_f32_e32 v14, v19, v20
	v_cvt_pk_bf16_f32 v0, v0, v1
	v_mul_f32_e32 v12, v5, v12
	v_mul_f32_e32 v13, v6, v13
	v_mul_f32_e32 v14, v7, v14
	global_store_short v[10:11], v0, off
	v_cvt_pk_bf16_f32 v0, v12, v1
	global_store_short v[10:11], v0, off offset:64
	v_cvt_pk_bf16_f32 v0, v13, v1
	global_store_short v[10:11], v0, off offset:128
	v_cvt_pk_bf16_f32 v14, v14, v1
	ds_read2_b32 v[12:13], v8 offset0:27 offset1:59
	global_store_short v[10:11], v14, off offset:192
	s_waitcnt lgkmcnt(0)
	v_mul_f32_e32 v8, v129, v13
	v_mul_f32_e32 v0, v145, v13
	v_fma_f32 v8, v65, v12, -v8
	v_mul_f32_e32 v15, v113, v13
	v_fma_f32 v16, v49, v12, -v0
	v_mul_f32_e32 v0, v8, v8
	v_mul_f32_e32 v13, v33, v13
	v_fma_f32 v15, v81, v12, -v15
	v_fmac_f32_e32 v0, v16, v16
	v_fma_f32 v12, v97, v12, -v13
	v_fmac_f32_e32 v0, v15, v15
	v_fmac_f32_e32 v0, v12, v12
	s_nop 1
	v_add_f32_dpp v0, v0, v0 quad_perm:[1,0,3,2] row_mask:0xf bank_mask:0xf
	s_nop 1
	v_add_f32_dpp v0, v0, v0 quad_perm:[2,3,0,1] row_mask:0xf bank_mask:0xf
	s_nop 1
	v_add_f32_dpp v0, v0, v0 row_half_mirror row_mask:0xf bank_mask:0xf
	s_nop 1
	v_add_f32_dpp v0, v0, v0 row_mirror row_mask:0xf bank_mask:0xf
	ds_swizzle_b32 v13, v0 offset:swizzle(SWAP,16)
	s_waitcnt lgkmcnt(0)
	v_add_f32_e32 v0, v0, v13
	v_fmamk_f32 v0, v0, 0x3c000000, v194
	v_rsq_f32_e32 v13, v0
	v_or_b32_e32 v0, 0xd800, v9
	v_lshl_add_u64 v[2:3], v[2:3], 0, v[0:1]
	v_mul_f32_e32 v0, v16, v13
	v_mul_f32_e32 v0, v4, v0
	v_mul_f32_e32 v8, v8, v13
	v_cvt_pk_bf16_f32 v0, v0, v1
	v_mul_f32_e32 v9, v15, v13
	v_mul_f32_e32 v4, v5, v8
	global_store_short v[2:3], v0, off
	v_cvt_pk_bf16_f32 v0, v4, v1
	v_mul_f32_e32 v10, v12, v13
	v_mul_f32_e32 v5, v6, v9
	global_store_short v[2:3], v0, off offset:64
	v_cvt_pk_bf16_f32 v0, v5, v1
	v_mul_f32_e32 v6, v7, v10
	global_store_short v[2:3], v0, off offset:128
	v_cvt_pk_bf16_f32 v0, v6, v1
	global_store_short v[2:3], v0, off offset:192
	s_cbranch_vccnz .LBB0_282
